# dilated attention: next-unit prefetch issued before the staging barrier instead of after it
# speedup vs baseline: 1.0016x; 1.0016x over previous
.Lzd_L1:
	s_waitcnt lgkmcnt(0)
	s_add_i32 s100, s40, 1
	s_cmp_lt_u32 s100, 16
	s_cbranch_scc1 .Lpf_L1
.Lpfret_L1:
	s_barrier
	s_cmp_eq_u32 s15, 0
	s_cselect_b32 s12, 2, 0
	s_max_i32 s12, s30, s12
	s_cmp_gt_i32 s12, s31
	s_cbranch_scc1 .LBB0_1729
	s_mul_i32 s13, s12, 0x3000
	s_add_i32 s43, s12, -1
	v_add_u32_e32 v4, s13, v126
	s_lshl_b32 s13, s12, 6
	s_mulk_i32 s12, 0x2400
	s_add_i32 s16, s42, 0xffffff9f
	v_add_u32_e32 v3, 0xffffff80, v120
	s_add_i32 s44, s14, s13
	v_add_u32_e32 v5, s12, v127

.Lpfret_L3:
	s_barrier
	s_cmp_eq_u32 s13, 0
	s_cselect_b32 s10, 2, 0
	s_max_i32 s10, s30, s10
	s_cmp_gt_i32 s10, s31
	s_cbranch_scc1 .LBB0_3830
	s_mul_i32 s11, s10, 0x3000
	s_add_i32 s43, s10, -1
	v_add_u32_e32 v4, s11, v126
	s_lshl_b32 s11, s10, 6
	s_mulk_i32 s10, 0x2400
	s_add_i32 s14, s42, 0xffffff9f
	v_add_u32_e32 v3, 0xffffff80, v120
	s_add_i32 s44, s12, s11
	v_add_u32_e32 v5, s10, v127
